# NSA compression MLP first GEMM: 32 loads of an 8-k-step group issued together with counted vmcnt (was 2 vmcnt(0) round trips per k-step); NSA units wait on these
# speedup vs baseline: 1.0094x; 1.0032x over previous
.LBB0_1780:
	v_min_u32_e32 v0, 0x1fff, v40
	v_mul_u32_u24_e32 v0, 0xb00, v0
	v_lshlrev_b32_e32 v0, 1, v0
	v_lshl_add_u64 v[20:21], v[28:29], 0, v[0:1]
	v_add_u32_e32 v0, 1, v40
	v_min_u32_e32 v0, 0x1fff, v0
	v_mul_u32_u24_e32 v0, 0xb00, v0
	v_lshlrev_b32_e32 v0, 1, v0
	v_lshl_add_u64 v[22:23], v[28:29], 0, v[0:1]
	v_lshl_add_u64 v[18:19], v[32:33], 0, s[6:7]
	global_load_dwordx4 v[52:55], v[20:21], off
	global_load_dwordx4 v[84:87], v[18:19], off
	global_load_dwordx4 v[116:119], v[18:19], off offset:16
	global_load_dwordx4 v[148:151], v[30:31], off offset:-128
	global_load_dwordx4 v[56:59], v[20:21], off offset:32
	global_load_dwordx4 v[88:91], v[18:19], off offset:64
	global_load_dwordx4 v[120:123], v[18:19], off offset:80
	global_load_dwordx4 v[152:155], v[30:31], off offset:-96
	global_load_dwordx4 v[60:63], v[20:21], off offset:64
	global_load_dwordx4 v[92:95], v[18:19], off offset:128
	global_load_dwordx4 v[124:127], v[18:19], off offset:144
	global_load_dwordx4 v[156:159], v[30:31], off offset:-64
	global_load_dwordx4 v[64:67], v[20:21], off offset:96
	global_load_dwordx4 v[96:99], v[18:19], off offset:192
	global_load_dwordx4 v[128:131], v[18:19], off offset:208
	global_load_dwordx4 v[160:163], v[30:31], off offset:-32
	global_load_dwordx4 v[68:71], v[22:23], off
	global_load_dwordx4 v[100:103], v[18:19], off offset:256
	global_load_dwordx4 v[132:135], v[18:19], off offset:272
	global_load_dwordx4 v[164:167], v[30:31], off
	global_load_dwordx4 v[72:75], v[22:23], off offset:32
	global_load_dwordx4 v[104:107], v[18:19], off offset:320
	global_load_dwordx4 v[136:139], v[18:19], off offset:336
	global_load_dwordx4 v[168:171], v[30:31], off offset:32
	global_load_dwordx4 v[76:79], v[22:23], off offset:64
	global_load_dwordx4 v[108:111], v[18:19], off offset:384
	global_load_dwordx4 v[140:143], v[18:19], off offset:400
	global_load_dwordx4 v[176:179], v[30:31], off offset:64
	global_load_dwordx4 v[80:83], v[22:23], off offset:96
	global_load_dwordx4 v[112:115], v[18:19], off offset:448
	global_load_dwordx4 v[144:147], v[18:19], off offset:464
	global_load_dwordx4 v[186:189], v[30:31], off offset:96
	s_add_u32 s6, s6, 0x200
	s_addc_u32 s7, s7, 0
	s_mov_b64 s[20:21], 0x100
	v_add_u32_e32 v40, 2, v40
	s_waitcnt vmcnt(28)
	v_lshlrev_b32_e32 v180, 16, v52
	v_and_b32_e32 v181, 0xffff0000, v52
	v_pk_add_f32 v[84:85], v[84:85], v[180:181]
	v_lshlrev_b32_e32 v182, 16, v53
	v_and_b32_e32 v183, 0xffff0000, v53
	v_pk_add_f32 v[86:87], v[86:87], v[182:183]
	v_lshlrev_b32_e32 v180, 16, v54
	v_and_b32_e32 v181, 0xffff0000, v54
	v_pk_add_f32 v[116:117], v[116:117], v[180:181]
	v_lshlrev_b32_e32 v182, 16, v55
	v_and_b32_e32 v183, 0xffff0000, v55
	v_pk_add_f32 v[118:119], v[118:119], v[182:183]
	v_cvt_pk_bf16_f32 v52, v84, v85
	v_cvt_pk_bf16_f32 v53, v86, v87
	v_cvt_pk_bf16_f32 v54, v116, v117
	v_cvt_pk_bf16_f32 v55, v118, v119
	s_nop 1
	v_mfma_f32_32x32x16_bf16 v[2:17], v[52:55], v[148:151], v[2:17]
	s_waitcnt vmcnt(24)
	v_lshlrev_b32_e32 v180, 16, v56
	v_and_b32_e32 v181, 0xffff0000, v56
	v_pk_add_f32 v[88:89], v[88:89], v[180:181]
	v_lshlrev_b32_e32 v182, 16, v57
	v_and_b32_e32 v183, 0xffff0000, v57
	v_pk_add_f32 v[90:91], v[90:91], v[182:183]
	v_lshlrev_b32_e32 v180, 16, v58
	v_and_b32_e32 v181, 0xffff0000, v58
	v_pk_add_f32 v[120:121], v[120:121], v[180:181]
	v_lshlrev_b32_e32 v182, 16, v59
	v_and_b32_e32 v183, 0xffff0000, v59
	v_pk_add_f32 v[122:123], v[122:123], v[182:183]
	v_cvt_pk_bf16_f32 v56, v88, v89
	v_cvt_pk_bf16_f32 v57, v90, v91
	v_cvt_pk_bf16_f32 v58, v120, v121
	v_cvt_pk_bf16_f32 v59, v122, v123
	s_nop 1
	v_mfma_f32_32x32x16_bf16 v[2:17], v[56:59], v[152:155], v[2:17]
	s_waitcnt vmcnt(20)
	v_lshlrev_b32_e32 v180, 16, v60
	v_and_b32_e32 v181, 0xffff0000, v60
	v_pk_add_f32 v[92:93], v[92:93], v[180:181]
	v_lshlrev_b32_e32 v182, 16, v61
	v_and_b32_e32 v183, 0xffff0000, v61
	v_pk_add_f32 v[94:95], v[94:95], v[182:183]
	v_lshlrev_b32_e32 v180, 16, v62
	v_and_b32_e32 v181, 0xffff0000, v62
	v_pk_add_f32 v[124:125], v[124:125], v[180:181]
	v_lshlrev_b32_e32 v182, 16, v63
	v_and_b32_e32 v183, 0xffff0000, v63
	v_pk_add_f32 v[126:127], v[126:127], v[182:183]
	v_cvt_pk_bf16_f32 v60, v92, v93
	v_cvt_pk_bf16_f32 v61, v94, v95
	v_cvt_pk_bf16_f32 v62, v124, v125
	v_cvt_pk_bf16_f32 v63, v126, v127
	s_nop 1
	v_mfma_f32_32x32x16_bf16 v[2:17], v[60:63], v[156:159], v[2:17]
	s_waitcnt vmcnt(16)
	v_lshlrev_b32_e32 v180, 16, v64
	v_and_b32_e32 v181, 0xffff0000, v64
	v_pk_add_f32 v[96:97], v[96:97], v[180:181]
	v_lshlrev_b32_e32 v182, 16, v65
	v_and_b32_e32 v183, 0xffff0000, v65
	v_pk_add_f32 v[98:99], v[98:99], v[182:183]
	v_lshlrev_b32_e32 v180, 16, v66
	v_and_b32_e32 v181, 0xffff0000, v66
	v_pk_add_f32 v[128:129], v[128:129], v[180:181]
	v_lshlrev_b32_e32 v182, 16, v67
	v_and_b32_e32 v183, 0xffff0000, v67
	v_pk_add_f32 v[130:131], v[130:131], v[182:183]
	v_cvt_pk_bf16_f32 v64, v96, v97
	v_cvt_pk_bf16_f32 v65, v98, v99
	v_cvt_pk_bf16_f32 v66, v128, v129
	v_cvt_pk_bf16_f32 v67, v130, v131
	s_nop 1
	v_mfma_f32_32x32x16_bf16 v[2:17], v[64:67], v[160:163], v[2:17]
	s_waitcnt vmcnt(12)
	v_lshlrev_b32_e32 v180, 16, v68
	v_and_b32_e32 v181, 0xffff0000, v68
	v_pk_add_f32 v[100:101], v[100:101], v[180:181]
	v_lshlrev_b32_e32 v182, 16, v69
	v_and_b32_e32 v183, 0xffff0000, v69
	v_pk_add_f32 v[102:103], v[102:103], v[182:183]
	v_lshlrev_b32_e32 v180, 16, v70
	v_and_b32_e32 v181, 0xffff0000, v70
	v_pk_add_f32 v[132:133], v[132:133], v[180:181]
	v_lshlrev_b32_e32 v182, 16, v71
	v_and_b32_e32 v183, 0xffff0000, v71
	v_pk_add_f32 v[134:135], v[134:135], v[182:183]
	v_cvt_pk_bf16_f32 v68, v100, v101
	v_cvt_pk_bf16_f32 v69, v102, v103
	v_cvt_pk_bf16_f32 v70, v132, v133
	v_cvt_pk_bf16_f32 v71, v134, v135
	s_nop 1
	v_mfma_f32_32x32x16_bf16 v[2:17], v[68:71], v[164:167], v[2:17]
	s_waitcnt vmcnt(8)
	v_lshlrev_b32_e32 v180, 16, v72
	v_and_b32_e32 v181, 0xffff0000, v72
	v_pk_add_f32 v[104:105], v[104:105], v[180:181]
	v_lshlrev_b32_e32 v182, 16, v73
	v_and_b32_e32 v183, 0xffff0000, v73
	v_pk_add_f32 v[106:107], v[106:107], v[182:183]
	v_lshlrev_b32_e32 v180, 16, v74
	v_and_b32_e32 v181, 0xffff0000, v74
	v_pk_add_f32 v[136:137], v[136:137], v[180:181]
	v_lshlrev_b32_e32 v182, 16, v75
	v_and_b32_e32 v183, 0xffff0000, v75
	v_pk_add_f32 v[138:139], v[138:139], v[182:183]
	v_cvt_pk_bf16_f32 v72, v104, v105
	v_cvt_pk_bf16_f32 v73, v106, v107
	v_cvt_pk_bf16_f32 v74, v136, v137
	v_cvt_pk_bf16_f32 v75, v138, v139
	s_nop 1
	v_mfma_f32_32x32x16_bf16 v[2:17], v[72:75], v[168:171], v[2:17]
	s_waitcnt vmcnt(4)
	v_lshlrev_b32_e32 v180, 16, v76
	v_and_b32_e32 v181, 0xffff0000, v76
	v_pk_add_f32 v[108:109], v[108:109], v[180:181]
	v_lshlrev_b32_e32 v182, 16, v77
	v_and_b32_e32 v183, 0xffff0000, v77
	v_pk_add_f32 v[110:111], v[110:111], v[182:183]
	v_lshlrev_b32_e32 v180, 16, v78
	v_and_b32_e32 v181, 0xffff0000, v78
	v_pk_add_f32 v[140:141], v[140:141], v[180:181]
	v_lshlrev_b32_e32 v182, 16, v79
	v_and_b32_e32 v183, 0xffff0000, v79
	v_pk_add_f32 v[142:143], v[142:143], v[182:183]
	v_cvt_pk_bf16_f32 v76, v108, v109
	v_cvt_pk_bf16_f32 v77, v110, v111
	v_cvt_pk_bf16_f32 v78, v140, v141
	v_cvt_pk_bf16_f32 v79, v142, v143
	s_nop 1
	v_mfma_f32_32x32x16_bf16 v[2:17], v[76:79], v[176:179], v[2:17]
	s_waitcnt vmcnt(0)
	v_lshlrev_b32_e32 v180, 16, v80
	v_and_b32_e32 v181, 0xffff0000, v80
	v_pk_add_f32 v[112:113], v[112:113], v[180:181]
	v_lshlrev_b32_e32 v182, 16, v81
	v_and_b32_e32 v183, 0xffff0000, v81
	v_pk_add_f32 v[114:115], v[114:115], v[182:183]
	v_lshlrev_b32_e32 v180, 16, v82
	v_and_b32_e32 v181, 0xffff0000, v82
	v_pk_add_f32 v[144:145], v[144:145], v[180:181]
	v_lshlrev_b32_e32 v182, 16, v83
	v_and_b32_e32 v183, 0xffff0000, v83
	v_pk_add_f32 v[146:147], v[146:147], v[182:183]
	v_cvt_pk_bf16_f32 v80, v112, v113
	v_cvt_pk_bf16_f32 v81, v114, v115
	v_cvt_pk_bf16_f32 v82, v144, v145
	v_cvt_pk_bf16_f32 v83, v146, v147
	s_nop 1
	v_mfma_f32_32x32x16_bf16 v[2:17], v[80:83], v[186:189], v[2:17]
	v_lshl_add_u64 v[30:31], v[30:31], 0, s[20:21]
	s_cmpk_eq_i32 s6, 0x2000
	s_cbranch_scc0 .LBB0_1780
	s_lshl_b32 s6, s94, 8
	s_mov_b32 s7, s95
	s_lshl_b64 s[6:7], s[6:7], 2
	s_add_u32 s6, s18, s6
	s_addc_u32 s7, s19, s7
	v_lshl_add_u64 v[18:19], v[26:27], 2, s[6:7]
	global_load_dword v0, v[18:19], off
	v_lshl_add_u32 v18, v26, 1, 0
	s_movk_i32 s6, 0x840
	v_lshl_or_b32 v30, v36, 2, 1
	v_cmp_gt_i32_e32 vcc, 2, v39
	s_waitcnt vmcnt(0)
	v_add_f32_e32 v2, v2, v0
	v_mul_f32_e32 v19, 0x3d372713, v2
	v_mul_f32_e32 v19, v2, v19
	v_fma_f32 v19, v2, v19, v2
	v_mul_f32_e32 v19, 0x3f4c422a, v19
	v_mul_f32_e32 v19, 0xc038aa3b, v19
	v_exp_f32_e32 v19, v19
	s_nop 0
	v_add_f32_e32 v19, 1.0, v19
	v_rcp_f32_e32 v19, v19
	s_nop 0
	v_mul_f32_e32 v2, v2, v19
	v_cvt_pk_bf16_f32 v2, v2, s0
	v_mad_u32_u24 v19, v36, s6, v18
	ds_write_b16 v19, v2
	v_add_f32_e32 v2, v3, v0
	v_mul_f32_e32 v3, 0x3d372713, v2
	v_mul_f32_e32 v3, v2, v3
	v_fma_f32 v3, v2, v3, v2
	v_mul_f32_e32 v3, 0x3f4c422a, v3
	v_mul_f32_e32 v3, 0xc038aa3b, v3
	v_exp_f32_e32 v3, v3
	s_movk_i32 s6, 0x210
	v_add_f32_e32 v3, 1.0, v3
	v_rcp_f32_e32 v3, v3
	s_nop 0
	v_mul_f32_e32 v2, v2, v3
	v_cvt_pk_bf16_f32 v3, v2, s0
	v_mad_u32_u24 v2, v30, s6, v18
	ds_write_b16 v2, v3
	v_add_f32_e32 v3, v4, v0
	v_mul_f32_e32 v4, 0x3d372713, v3
	v_mul_f32_e32 v4, v3, v4
	v_fma_f32 v4, v3, v4, v3
	v_mul_f32_e32 v4, 0x3f4c422a, v4
	v_mul_f32_e32 v4, 0xc038aa3b, v4
	v_exp_f32_e32 v4, v4
	s_nop 0
	v_add_f32_e32 v4, 1.0, v4
	v_rcp_f32_e32 v4, v4
	s_nop 0
	v_mul_f32_e32 v3, v3, v4
	v_cvt_pk_bf16_f32 v3, v3, s0
	ds_write_b16 v2, v3 offset:528
	v_add_f32_e32 v3, v5, v0
	v_mul_f32_e32 v4, 0x3d372713, v3
	v_mul_f32_e32 v4, v3, v4
	v_fma_f32 v4, v3, v4, v3
	v_mul_f32_e32 v4, 0x3f4c422a, v4
	v_mul_f32_e32 v4, 0xc038aa3b, v4
	v_exp_f32_e32 v4, v4
	s_nop 0
	v_add_f32_e32 v4, 1.0, v4
	v_rcp_f32_e32 v4, v4
	s_nop 0
	v_mul_f32_e32 v3, v3, v4
	v_cvt_pk_bf16_f32 v3, v3, s0
	ds_write_b16 v2, v3 offset:1056
	v_add_f32_e32 v3, v6, v0
	v_mul_f32_e32 v4, 0x3d372713, v3
	v_mul_f32_e32 v4, v3, v4
	v_fma_f32 v4, v3, v4, v3
	v_mul_f32_e32 v4, 0x3f4c422a, v4
	v_mul_f32_e32 v4, 0xc038aa3b, v4
	v_exp_f32_e32 v4, v4
	s_nop 0
	v_add_f32_e32 v4, 1.0, v4
	v_rcp_f32_e32 v4, v4
	s_nop 0
	v_mul_f32_e32 v3, v3, v4
	v_cvt_pk_bf16_f32 v3, v3, s0
	ds_write_b16 v2, v3 offset:3696
	v_add_f32_e32 v3, v7, v0
	v_mul_f32_e32 v4, 0x3d372713, v3
	v_mul_f32_e32 v4, v3, v4
	v_fma_f32 v4, v3, v4, v3
	v_mul_f32_e32 v4, 0x3f4c422a, v4
	v_mul_f32_e32 v4, 0xc038aa3b, v4
	v_exp_f32_e32 v4, v4
	s_nop 0
	v_add_f32_e32 v4, 1.0, v4
	v_rcp_f32_e32 v4, v4
	s_nop 0
	v_mul_f32_e32 v3, v3, v4
	v_cvt_pk_bf16_f32 v3, v3, s0
	ds_write_b16 v2, v3 offset:4224
	v_add_f32_e32 v3, v8, v0
	v_mul_f32_e32 v4, 0x3d372713, v3
	v_mul_f32_e32 v4, v3, v4
	v_fma_f32 v4, v3, v4, v3
	v_mul_f32_e32 v4, 0x3f4c422a, v4
	v_mul_f32_e32 v4, 0xc038aa3b, v4
	v_exp_f32_e32 v4, v4
	s_nop 0
	v_add_f32_e32 v4, 1.0, v4
	v_rcp_f32_e32 v4, v4
	s_nop 0
	v_mul_f32_e32 v3, v3, v4
	v_cvt_pk_bf16_f32 v3, v3, s0
	ds_write_b16 v2, v3 offset:4752
	v_add_f32_e32 v3, v9, v0
	v_mul_f32_e32 v4, 0x3d372713, v3
	v_mul_f32_e32 v4, v3, v4
	v_fma_f32 v4, v3, v4, v3
	v_mul_f32_e32 v4, 0x3f4c422a, v4
	v_mul_f32_e32 v4, 0xc038aa3b, v4
	v_exp_f32_e32 v4, v4
	s_nop 0
	v_add_f32_e32 v4, 1.0, v4
	v_rcp_f32_e32 v4, v4
	s_nop 0
	v_mul_f32_e32 v3, v3, v4
	v_cvt_pk_bf16_f32 v3, v3, s0
	ds_write_b16 v2, v3 offset:5280
	v_add_f32_e32 v3, v10, v0
	v_mul_f32_e32 v4, 0x3d372713, v3
	v_mul_f32_e32 v4, v3, v4
	v_fma_f32 v4, v3, v4, v3
	v_mul_f32_e32 v4, 0x3f4c422a, v4
	v_mul_f32_e32 v4, 0xc038aa3b, v4
	v_exp_f32_e32 v4, v4
	s_nop 0
	v_add_f32_e32 v4, 1.0, v4
	v_rcp_f32_e32 v4, v4
	s_nop 0
	v_mul_f32_e32 v3, v3, v4
	v_cvt_pk_bf16_f32 v3, v3, s0
	ds_write_b16 v2, v3 offset:7920
	v_add_f32_e32 v3, v11, v0
	v_mul_f32_e32 v4, 0x3d372713, v3
	v_mul_f32_e32 v4, v3, v4
	v_fma_f32 v4, v3, v4, v3
	v_mul_f32_e32 v4, 0x3f4c422a, v4
	v_mul_f32_e32 v4, 0xc038aa3b, v4
	v_exp_f32_e32 v4, v4
	s_nop 0
	v_add_f32_e32 v4, 1.0, v4
	v_rcp_f32_e32 v4, v4
	s_nop 0
	v_mul_f32_e32 v3, v3, v4
	v_cvt_pk_bf16_f32 v3, v3, s0
	ds_write_b16 v2, v3 offset:8448
	v_add_f32_e32 v3, v12, v0
	v_mul_f32_e32 v4, 0x3d372713, v3
	v_mul_f32_e32 v4, v3, v4
	v_fma_f32 v4, v3, v4, v3
	v_mul_f32_e32 v4, 0x3f4c422a, v4
	v_mul_f32_e32 v4, 0xc038aa3b, v4
	v_exp_f32_e32 v4, v4
	s_nop 0
	v_add_f32_e32 v4, 1.0, v4
	v_rcp_f32_e32 v4, v4
	s_nop 0
	v_mul_f32_e32 v3, v3, v4
	v_cvt_pk_bf16_f32 v3, v3, s0
	ds_write_b16 v2, v3 offset:8976
	v_add_f32_e32 v3, v13, v0
	v_mul_f32_e32 v4, 0x3d372713, v3
	v_mul_f32_e32 v4, v3, v4
	v_fma_f32 v4, v3, v4, v3
	v_mul_f32_e32 v4, 0x3f4c422a, v4
	v_mul_f32_e32 v4, 0xc038aa3b, v4
	v_exp_f32_e32 v4, v4
	s_nop 0
	v_add_f32_e32 v4, 1.0, v4
	v_rcp_f32_e32 v4, v4
	s_nop 0
	v_mul_f32_e32 v3, v3, v4
	v_cvt_pk_bf16_f32 v3, v3, s0
	ds_write_b16 v2, v3 offset:9504
	v_add_f32_e32 v3, v14, v0
	v_mul_f32_e32 v4, 0x3d372713, v3
	v_mul_f32_e32 v4, v3, v4
	v_fma_f32 v4, v3, v4, v3
	v_mul_f32_e32 v4, 0x3f4c422a, v4
	v_mul_f32_e32 v4, 0xc038aa3b, v4
	v_exp_f32_e32 v4, v4
	s_nop 0
	v_add_f32_e32 v4, 1.0, v4
	v_rcp_f32_e32 v4, v4
	s_nop 0
	v_mul_f32_e32 v3, v3, v4
	v_cvt_pk_bf16_f32 v3, v3, s0
	ds_write_b16 v2, v3 offset:12144
	v_add_f32_e32 v3, v15, v0
	v_mul_f32_e32 v4, 0x3d372713, v3
	v_mul_f32_e32 v4, v3, v4
	v_fma_f32 v4, v3, v4, v3
	v_mul_f32_e32 v4, 0x3f4c422a, v4
	v_mul_f32_e32 v4, 0xc038aa3b, v4
	v_exp_f32_e32 v4, v4
	s_nop 0
	v_add_f32_e32 v4, 1.0, v4
	v_rcp_f32_e32 v4, v4
	s_nop 0
	v_mul_f32_e32 v3, v3, v4
	v_cvt_pk_bf16_f32 v3, v3, s0
	ds_write_b16 v2, v3 offset:12672
	v_add_f32_e32 v3, v16, v0
	v_mul_f32_e32 v4, 0x3d372713, v3
	v_mul_f32_e32 v4, v3, v4
	v_fma_f32 v4, v3, v4, v3
	v_mul_f32_e32 v4, 0x3f4c422a, v4
	v_mul_f32_e32 v4, 0xc038aa3b, v4
	v_exp_f32_e32 v4, v4
	v_add_f32_e32 v0, v17, v0
	v_add_f32_e32 v4, 1.0, v4
	v_rcp_f32_e32 v4, v4
	s_nop 0
	v_mul_f32_e32 v3, v3, v4
	v_cvt_pk_bf16_f32 v3, v3, s0
	ds_write_b16 v2, v3 offset:13200
	v_mul_f32_e32 v3, 0x3d372713, v0
	v_mul_f32_e32 v3, v0, v3
	v_fma_f32 v3, v0, v3, v0
	v_mul_f32_e32 v3, 0x3f4c422a, v3
	v_mul_f32_e32 v3, 0xc038aa3b, v3
	v_exp_f32_e32 v3, v3
	s_nop 0
	v_add_f32_e32 v3, 1.0, v3
	v_rcp_f32_e32 v3, v3
	s_nop 0
	v_mul_f32_e32 v0, v0, v3
	v_cvt_pk_bf16_f32 v0, v0, s0
	ds_write_b16 v2, v0 offset:13728
	s_waitcnt lgkmcnt(0)
	s_barrier
	s_and_saveexec_b64 s[6:7], vcc
	s_mov_b32 s28, 0x40c00000
	s_cbranch_execz .LBB0_1783
	s_lshl_b64 s[18:19], s[94:95], 16
	s_add_u32 s18, s8, s18
	s_addc_u32 s19, s9, s19
	s_lshl_b32 s94, s94, 6
	s_lshl_b64 s[8:9], s[94:95], 2
	s_add_u32 s8, s16, s8
	s_movk_i32 s16, 0x210
	v_mad_u32_u24 v31, v38, s16, 0
	v_lshlrev_b64 v[22:23], 2, v[26:27]
	v_lshl_add_u32 v0, v36, 4, v31
	v_lshl_add_u64 v[24:25], s[18:19], 0, v[22:23]
	ds_read_b128 v[2:5], v0
	v_lshlrev_b32_e32 v0, 11, v36
	v_lshl_add_u64 v[28:29], v[24:25], 0, v[0:1]
	global_load_dword v0, v[28:29], off
	global_load_dword v6, v[28:29], off offset:256
	global_load_dword v7, v[28:29], off offset:512
	global_load_dword v8, v[28:29], off offset:768
	global_load_dword v9, v[28:29], off offset:1024
	global_load_dword v10, v[28:29], off offset:1280
	global_load_dword v11, v[28:29], off offset:1536
	global_load_dword v12, v[28:29], off offset:1792
	s_movk_i32 s16, 0x1000
	s_addc_u32 s9, s17, s9
	s_waitcnt vmcnt(6)
	v_cvt_pk_bf16_f32 v6, v0, v6
	v_or_b32_e32 v0, 16, v37
	v_lshl_add_u32 v18, v0, 1, v31
	v_lshlrev_b32_e32 v0, 8, v0
	v_lshl_add_u64 v[32:33], v[24:25], 0, v[0:1]
	global_load_dword v0, v[32:33], off
	v_add_co_u32_e32 v32, vcc, s16, v28
	ds_read_b128 v[18:21], v18
	s_nop 0
	v_addc_co_u32_e32 v33, vcc, 0, v29, vcc
	global_load_dword v27, v[32:33], off offset:256
	global_load_dword v39, v[32:33], off offset:512
	global_load_dword v40, v[32:33], off offset:768
	global_load_dword v41, v[32:33], off offset:1024
	global_load_dword v42, v[32:33], off offset:1280
	global_load_dword v43, v[32:33], off offset:1536
	s_nop 0
	global_load_dword v32, v[32:33], off offset:1792
	s_waitcnt vmcnt(12)
	v_cvt_pk_bf16_f32 v7, v7, v8
	s_waitcnt vmcnt(10)
	v_cvt_pk_bf16_f32 v8, v9, v10
	s_waitcnt vmcnt(8)
	v_cvt_pk_bf16_f32 v9, v11, v12
	s_movk_i32 s16, 0x3000
	s_waitcnt vmcnt(6)
	v_cvt_pk_bf16_f32 v38, v0, v27
	s_waitcnt lgkmcnt(1)
	v_mfma_f32_32x32x16_bf16 v[2:17], v[2:5], v[6:9], 0
	s_waitcnt vmcnt(4)
	v_cvt_pk_bf16_f32 v39, v39, v40
	v_or_b32_e32 v0, 32, v37
	s_waitcnt vmcnt(2)
	v_cvt_pk_bf16_f32 v40, v41, v42
	s_waitcnt vmcnt(0)
	v_cvt_pk_bf16_f32 v41, v43, v32
	s_waitcnt lgkmcnt(0)
	s_nop 0
	v_mfma_f32_32x32x16_bf16 v[2:17], v[18:21], v[38:41], v[2:17]
	v_lshl_add_u32 v18, v0, 1, v31
	v_lshlrev_b32_e32 v0, 8, v0
	v_lshl_add_u64 v[32:33], v[24:25], 0, v[0:1]
	global_load_dword v0, v[32:33], off
	v_add_co_u32_e32 v32, vcc, s25, v28
	ds_read_b128 v[18:21], v18
	s_nop 0
	v_addc_co_u32_e32 v33, vcc, 0, v29, vcc
	global_load_dword v27, v[32:33], off offset:256
	global_load_dword v39, v[32:33], off offset:512
	global_load_dword v40, v[32:33], off offset:768
	global_load_dword v41, v[32:33], off offset:1024
	global_load_dword v42, v[32:33], off offset:1280
	global_load_dword v43, v[32:33], off offset:1536
	s_nop 0
	global_load_dword v32, v[32:33], off offset:1792
	s_waitcnt vmcnt(6)
	v_cvt_pk_bf16_f32 v38, v0, v27
	v_or_b32_e32 v0, 48, v37
	s_waitcnt vmcnt(4)
	v_cvt_pk_bf16_f32 v39, v39, v40
	s_waitcnt vmcnt(2)
	v_cvt_pk_bf16_f32 v40, v41, v42
	s_waitcnt vmcnt(0)
	v_cvt_pk_bf16_f32 v41, v43, v32
	s_waitcnt lgkmcnt(0)
	s_nop 0
	v_mfma_f32_32x32x16_bf16 v[2:17], v[18:21], v[38:41], v[2:17]
	v_lshl_add_u32 v18, v0, 1, v31
	v_lshlrev_b32_e32 v0, 8, v0
	v_lshl_add_u64 v[32:33], v[24:25], 0, v[0:1]
	global_load_dword v0, v[32:33], off
	v_add_co_u32_e32 v32, vcc, s16, v28
	ds_read_b128 v[18:21], v18
	s_nop 0
	v_addc_co_u32_e32 v33, vcc, 0, v29, vcc
	global_load_dword v27, v[32:33], off offset:256
	global_load_dword v39, v[32:33], off offset:512
	global_load_dword v40, v[32:33], off offset:768
	global_load_dword v41, v[32:33], off offset:1024
	global_load_dword v42, v[32:33], off offset:1280
	global_load_dword v43, v[32:33], off offset:1536
	s_nop 0
	global_load_dword v32, v[32:33], off offset:1792
	s_movk_i32 s16, 0x4000
	s_waitcnt vmcnt(6)
	v_cvt_pk_bf16_f32 v38, v0, v27
	v_or_b32_e32 v0, 64, v37
	s_waitcnt vmcnt(4)
	v_cvt_pk_bf16_f32 v39, v39, v40
	s_waitcnt vmcnt(2)
	v_cvt_pk_bf16_f32 v40, v41, v42
	s_waitcnt vmcnt(0)
	v_cvt_pk_bf16_f32 v41, v43, v32
	s_waitcnt lgkmcnt(0)
	s_nop 0
	v_mfma_f32_32x32x16_bf16 v[2:17], v[18:21], v[38:41], v[2:17]
	v_lshl_add_u32 v18, v0, 1, v31
	v_lshlrev_b32_e32 v0, 8, v0
	v_lshl_add_u64 v[32:33], v[24:25], 0, v[0:1]
	global_load_dword v0, v[32:33], off
	v_add_co_u32_e32 v32, vcc, s16, v28
	ds_read_b128 v[18:21], v18
	s_nop 0
	v_addc_co_u32_e32 v33, vcc, 0, v29, vcc
	global_load_dword v27, v[32:33], off offset:256
	global_load_dword v39, v[32:33], off offset:512
	global_load_dword v40, v[32:33], off offset:768
	global_load_dword v41, v[32:33], off offset:1024
	global_load_dword v42, v[32:33], off offset:1280
	global_load_dword v43, v[32:33], off offset:1536
	s_nop 0
	global_load_dword v32, v[32:33], off offset:1792
	s_movk_i32 s16, 0x5000
	s_waitcnt vmcnt(6)
	v_cvt_pk_bf16_f32 v38, v0, v27
	v_or_b32_e32 v0, 0x50, v37
	s_waitcnt vmcnt(4)
	v_cvt_pk_bf16_f32 v39, v39, v40
	s_waitcnt vmcnt(2)
	v_cvt_pk_bf16_f32 v40, v41, v42
	s_waitcnt vmcnt(0)
	v_cvt_pk_bf16_f32 v41, v43, v32
	s_waitcnt lgkmcnt(0)
	s_nop 0
	v_mfma_f32_32x32x16_bf16 v[2:17], v[18:21], v[38:41], v[2:17]
	v_lshl_add_u32 v18, v0, 1, v31
	v_lshlrev_b32_e32 v0, 8, v0
	v_lshl_add_u64 v[32:33], v[24:25], 0, v[0:1]
	global_load_dword v0, v[32:33], off
	v_add_co_u32_e32 v32, vcc, s16, v28
	ds_read_b128 v[18:21], v18
	s_nop 0
	v_addc_co_u32_e32 v33, vcc, 0, v29, vcc
	global_load_dword v27, v[32:33], off offset:256
	global_load_dword v39, v[32:33], off offset:512
	global_load_dword v40, v[32:33], off offset:768
	global_load_dword v41, v[32:33], off offset:1024
	global_load_dword v42, v[32:33], off offset:1280
	global_load_dword v43, v[32:33], off offset:1536
	s_nop 0
	global_load_dword v32, v[32:33], off offset:1792
	s_movk_i32 s16, 0x6000
	s_waitcnt vmcnt(6)
	v_cvt_pk_bf16_f32 v38, v0, v27
	v_or_b32_e32 v0, 0x60, v37
	s_waitcnt vmcnt(4)
	v_cvt_pk_bf16_f32 v39, v39, v40
	s_waitcnt vmcnt(2)
	v_cvt_pk_bf16_f32 v40, v41, v42
	s_waitcnt vmcnt(0)
	v_cvt_pk_bf16_f32 v41, v43, v32
	s_waitcnt lgkmcnt(0)
	s_nop 0
	v_mfma_f32_32x32x16_bf16 v[2:17], v[18:21], v[38:41], v[2:17]
	v_lshl_add_u32 v18, v0, 1, v31
	v_lshlrev_b32_e32 v0, 8, v0
	v_lshl_add_u64 v[32:33], v[24:25], 0, v[0:1]
	global_load_dword v0, v[32:33], off
	v_add_co_u32_e32 v32, vcc, s16, v28
	ds_read_b128 v[18:21], v18
	s_nop 0
	v_addc_co_u32_e32 v33, vcc, 0, v29, vcc
	global_load_dword v27, v[32:33], off offset:256
	global_load_dword v39, v[32:33], off offset:512
	global_load_dword v40, v[32:33], off offset:768
	global_load_dword v41, v[32:33], off offset:1024
	global_load_dword v42, v[32:33], off offset:1280
	global_load_dword v43, v[32:33], off offset:1536
	s_nop 0
	global_load_dword v32, v[32:33], off offset:1792
	s_movk_i32 s16, 0x7000
	s_waitcnt vmcnt(6)
	v_cvt_pk_bf16_f32 v38, v0, v27
	v_or_b32_e32 v0, 0x70, v37
	s_waitcnt vmcnt(4)
	v_cvt_pk_bf16_f32 v39, v39, v40
	s_waitcnt vmcnt(2)
	v_cvt_pk_bf16_f32 v40, v41, v42
	s_waitcnt vmcnt(0)
	v_cvt_pk_bf16_f32 v41, v43, v32
	s_waitcnt lgkmcnt(0)
	s_nop 0
	v_mfma_f32_32x32x16_bf16 v[2:17], v[18:21], v[38:41], v[2:17]
	v_lshl_add_u32 v18, v0, 1, v31
	v_lshlrev_b32_e32 v0, 8, v0
	v_lshl_add_u64 v[32:33], v[24:25], 0, v[0:1]
	global_load_dword v0, v[32:33], off
	v_add_co_u32_e32 v32, vcc, s16, v28
	ds_read_b128 v[18:21], v18
	s_nop 0
	v_addc_co_u32_e32 v33, vcc, 0, v29, vcc
	global_load_dword v27, v[32:33], off offset:256
	global_load_dword v39, v[32:33], off offset:512
	global_load_dword v40, v[32:33], off offset:768
	global_load_dword v41, v[32:33], off offset:1024
	global_load_dword v42, v[32:33], off offset:1280
	global_load_dword v43, v[32:33], off offset:1536
	s_nop 0
	global_load_dword v32, v[32:33], off offset:1792
	s_mov_b32 s16, 0x9000
	s_waitcnt vmcnt(6)
	v_cvt_pk_bf16_f32 v38, v0, v27
	v_or_b32_e32 v0, 0x80, v37
	s_waitcnt vmcnt(4)
	v_cvt_pk_bf16_f32 v39, v39, v40
	s_waitcnt vmcnt(2)
	v_cvt_pk_bf16_f32 v40, v41, v42
	s_waitcnt vmcnt(0)
	v_cvt_pk_bf16_f32 v41, v43, v32
	s_waitcnt lgkmcnt(0)
	s_nop 0
	v_mfma_f32_32x32x16_bf16 v[2:17], v[18:21], v[38:41], v[2:17]
	v_lshl_add_u32 v18, v0, 1, v31
	v_lshlrev_b32_e32 v0, 8, v0
	v_lshl_add_u64 v[32:33], v[24:25], 0, v[0:1]
	global_load_dword v0, v[32:33], off
	v_add_co_u32_e32 v32, vcc, s54, v28
	ds_read_b128 v[18:21], v18
	s_nop 0
	v_addc_co_u32_e32 v33, vcc, 0, v29, vcc
	global_load_dword v27, v[32:33], off offset:256
	global_load_dword v39, v[32:33], off offset:512
	global_load_dword v40, v[32:33], off offset:768
	global_load_dword v41, v[32:33], off offset:1024
	global_load_dword v42, v[32:33], off offset:1280
	global_load_dword v43, v[32:33], off offset:1536
	s_nop 0
	global_load_dword v32, v[32:33], off offset:1792
	s_waitcnt vmcnt(6)
	v_cvt_pk_bf16_f32 v38, v0, v27
	v_or_b32_e32 v0, 0x90, v37
	s_waitcnt vmcnt(4)
	v_cvt_pk_bf16_f32 v39, v39, v40
	s_waitcnt vmcnt(2)
	v_cvt_pk_bf16_f32 v40, v41, v42
	s_waitcnt vmcnt(0)
	v_cvt_pk_bf16_f32 v41, v43, v32
	s_waitcnt lgkmcnt(0)
	s_nop 0
	v_mfma_f32_32x32x16_bf16 v[2:17], v[18:21], v[38:41], v[2:17]
	v_lshl_add_u32 v18, v0, 1, v31
	v_lshlrev_b32_e32 v0, 8, v0
	v_lshl_add_u64 v[32:33], v[24:25], 0, v[0:1]
	global_load_dword v0, v[32:33], off
	v_add_co_u32_e32 v32, vcc, s16, v28
	ds_read_b128 v[18:21], v18
	s_nop 0
	v_addc_co_u32_e32 v33, vcc, 0, v29, vcc
	global_load_dword v27, v[32:33], off offset:256
	global_load_dword v39, v[32:33], off offset:512
	global_load_dword v40, v[32:33], off offset:768
	global_load_dword v41, v[32:33], off offset:1024
	global_load_dword v42, v[32:33], off offset:1280
	global_load_dword v43, v[32:33], off offset:1536
	s_nop 0
	global_load_dword v32, v[32:33], off offset:1792
	s_mov_b32 s16, 0xa000
	s_waitcnt vmcnt(6)
	v_cvt_pk_bf16_f32 v38, v0, v27
	v_or_b32_e32 v0, 0xa0, v37
	s_waitcnt vmcnt(4)
	v_cvt_pk_bf16_f32 v39, v39, v40
	s_waitcnt vmcnt(2)
	v_cvt_pk_bf16_f32 v40, v41, v42
	s_waitcnt vmcnt(0)
	v_cvt_pk_bf16_f32 v41, v43, v32
	s_waitcnt lgkmcnt(0)
	s_nop 0
	v_mfma_f32_32x32x16_bf16 v[2:17], v[18:21], v[38:41], v[2:17]
	v_lshl_add_u32 v18, v0, 1, v31
	v_lshlrev_b32_e32 v0, 8, v0
	v_lshl_add_u64 v[32:33], v[24:25], 0, v[0:1]
	global_load_dword v0, v[32:33], off
	v_add_co_u32_e32 v32, vcc, s16, v28
	ds_read_b128 v[18:21], v18
	s_nop 0
	v_addc_co_u32_e32 v33, vcc, 0, v29, vcc
	global_load_dword v27, v[32:33], off offset:256
	global_load_dword v39, v[32:33], off offset:512
	global_load_dword v40, v[32:33], off offset:768
	global_load_dword v41, v[32:33], off offset:1024
	global_load_dword v42, v[32:33], off offset:1280
	global_load_dword v43, v[32:33], off offset:1536
	s_nop 0
	global_load_dword v32, v[32:33], off offset:1792
	s_mov_b32 s16, 0xb000
	s_waitcnt vmcnt(6)
	v_cvt_pk_bf16_f32 v38, v0, v27
	v_or_b32_e32 v0, 0xb0, v37
	s_waitcnt vmcnt(4)
	v_cvt_pk_bf16_f32 v39, v39, v40
	s_waitcnt vmcnt(2)
	v_cvt_pk_bf16_f32 v40, v41, v42
	s_waitcnt vmcnt(0)
	v_cvt_pk_bf16_f32 v41, v43, v32
	s_waitcnt lgkmcnt(0)
	s_nop 0
	v_mfma_f32_32x32x16_bf16 v[2:17], v[18:21], v[38:41], v[2:17]
	v_lshl_add_u32 v18, v0, 1, v31
	v_lshlrev_b32_e32 v0, 8, v0
	v_lshl_add_u64 v[32:33], v[24:25], 0, v[0:1]
	global_load_dword v0, v[32:33], off
	v_add_co_u32_e32 v32, vcc, s16, v28
	ds_read_b128 v[18:21], v18
	s_nop 0
	v_addc_co_u32_e32 v33, vcc, 0, v29, vcc
	global_load_dword v27, v[32:33], off offset:256
	global_load_dword v39, v[32:33], off offset:512
	global_load_dword v40, v[32:33], off offset:768
	global_load_dword v41, v[32:33], off offset:1024
	global_load_dword v42, v[32:33], off offset:1280
	global_load_dword v43, v[32:33], off offset:1536
	s_nop 0
	global_load_dword v32, v[32:33], off offset:1792
	s_mov_b32 s16, 0xc000
	s_waitcnt vmcnt(6)
	v_cvt_pk_bf16_f32 v38, v0, v27
	v_or_b32_e32 v0, 0xc0, v37
	s_waitcnt vmcnt(4)
	v_cvt_pk_bf16_f32 v39, v39, v40
	s_waitcnt vmcnt(2)
	v_cvt_pk_bf16_f32 v40, v41, v42
	s_waitcnt vmcnt(0)
	v_cvt_pk_bf16_f32 v41, v43, v32
	s_waitcnt lgkmcnt(0)
	s_nop 0
	v_mfma_f32_32x32x16_bf16 v[2:17], v[18:21], v[38:41], v[2:17]
	v_lshl_add_u32 v18, v0, 1, v31
	v_lshlrev_b32_e32 v0, 8, v0
	v_lshl_add_u64 v[32:33], v[24:25], 0, v[0:1]
	global_load_dword v0, v[32:33], off
	v_add_co_u32_e32 v32, vcc, s16, v28
	ds_read_b128 v[18:21], v18
	s_nop 0
	v_addc_co_u32_e32 v33, vcc, 0, v29, vcc
	global_load_dword v27, v[32:33], off offset:256
	global_load_dword v39, v[32:33], off offset:512
	global_load_dword v40, v[32:33], off offset:768
	global_load_dword v41, v[32:33], off offset:1024
	global_load_dword v42, v[32:33], off offset:1280
	global_load_dword v43, v[32:33], off offset:1536
	s_nop 0
	global_load_dword v32, v[32:33], off offset:1792
	s_mov_b32 s16, 0xd000
	s_waitcnt vmcnt(6)
	v_cvt_pk_bf16_f32 v38, v0, v27
	v_or_b32_e32 v0, 0xd0, v37
	s_waitcnt vmcnt(4)
	v_cvt_pk_bf16_f32 v39, v39, v40
	s_waitcnt vmcnt(2)
	v_cvt_pk_bf16_f32 v40, v41, v42
	s_waitcnt vmcnt(0)
	v_cvt_pk_bf16_f32 v41, v43, v32
	s_waitcnt lgkmcnt(0)
	s_nop 0
	v_mfma_f32_32x32x16_bf16 v[2:17], v[18:21], v[38:41], v[2:17]
	v_lshl_add_u32 v18, v0, 1, v31
	v_lshlrev_b32_e32 v0, 8, v0
	v_lshl_add_u64 v[32:33], v[24:25], 0, v[0:1]
	global_load_dword v0, v[32:33], off
	v_add_co_u32_e32 v32, vcc, s16, v28
	ds_read_b128 v[18:21], v18
	s_nop 0
	v_addc_co_u32_e32 v33, vcc, 0, v29, vcc
	global_load_dword v27, v[32:33], off offset:256
	global_load_dword v39, v[32:33], off offset:512
	global_load_dword v40, v[32:33], off offset:768
	global_load_dword v41, v[32:33], off offset:1024
	global_load_dword v42, v[32:33], off offset:1280
	global_load_dword v43, v[32:33], off offset:1536
	s_nop 0
	global_load_dword v32, v[32:33], off offset:1792
	s_mov_b32 s16, 0xe000
	s_waitcnt vmcnt(6)
	v_cvt_pk_bf16_f32 v38, v0, v27
	v_or_b32_e32 v0, 0xe0, v37
	s_waitcnt vmcnt(4)
	v_cvt_pk_bf16_f32 v39, v39, v40
	s_waitcnt vmcnt(2)
	v_cvt_pk_bf16_f32 v40, v41, v42
	s_waitcnt vmcnt(0)
	v_cvt_pk_bf16_f32 v41, v43, v32
	s_waitcnt lgkmcnt(0)
	s_nop 0
	v_mfma_f32_32x32x16_bf16 v[2:17], v[18:21], v[38:41], v[2:17]
	v_lshl_add_u32 v18, v0, 1, v31
	v_lshlrev_b32_e32 v0, 8, v0
	v_lshl_add_u64 v[32:33], v[24:25], 0, v[0:1]
	global_load_dword v0, v[32:33], off
	v_add_co_u32_e32 v32, vcc, s16, v28
	ds_read_b128 v[18:21], v18
	s_nop 0
	v_addc_co_u32_e32 v33, vcc, 0, v29, vcc
	global_load_dword v27, v[32:33], off offset:256
	global_load_dword v39, v[32:33], off offset:512
	global_load_dword v40, v[32:33], off offset:768
	global_load_dword v41, v[32:33], off offset:1024
	global_load_dword v42, v[32:33], off offset:1280
	global_load_dword v43, v[32:33], off offset:1536
	s_nop 0
	global_load_dword v32, v[32:33], off offset:1792
	s_mov_b32 s16, 0xf000
	s_waitcnt vmcnt(6)
	v_cvt_pk_bf16_f32 v38, v0, v27
	v_or_b32_e32 v0, 0xf0, v37
	s_waitcnt vmcnt(4)
	v_cvt_pk_bf16_f32 v39, v39, v40
	s_waitcnt vmcnt(2)
	v_cvt_pk_bf16_f32 v40, v41, v42
	s_waitcnt vmcnt(0)
	v_cvt_pk_bf16_f32 v41, v43, v32
	s_waitcnt lgkmcnt(0)
	s_nop 0
	v_mfma_f32_32x32x16_bf16 v[2:17], v[18:21], v[38:41], v[2:17]
	v_lshl_add_u32 v18, v0, 1, v31
	v_lshlrev_b32_e32 v0, 8, v0
	v_lshl_add_u64 v[24:25], v[24:25], 0, v[0:1]
	global_load_dword v0, v[24:25], off
	v_add_co_u32_e32 v24, vcc, s16, v28
	ds_read_b128 v[18:21], v18
	s_nop 0
	v_addc_co_u32_e32 v25, vcc, 0, v29, vcc
	global_load_dword v27, v[24:25], off offset:256
	global_load_dword v28, v[24:25], off offset:512
	global_load_dword v29, v[24:25], off offset:768
	global_load_dword v31, v[24:25], off offset:1024
	global_load_dword v32, v[24:25], off offset:1280
	global_load_dword v33, v[24:25], off offset:1536
	s_nop 0
	global_load_dword v24, v[24:25], off offset:1792
	s_waitcnt vmcnt(6)
	v_cvt_pk_bf16_f32 v38, v0, v27
	s_waitcnt vmcnt(4)
	v_cvt_pk_bf16_f32 v39, v28, v29
	s_waitcnt vmcnt(2)
	v_cvt_pk_bf16_f32 v40, v31, v32
	s_waitcnt vmcnt(0)
	v_cvt_pk_bf16_f32 v41, v33, v24
	s_waitcnt lgkmcnt(0)
	s_nop 0
	v_mfma_f32_32x32x16_bf16 v[2:17], v[18:21], v[38:41], v[2:17]
	v_lshl_add_u64 v[18:19], s[8:9], 0, v[22:23]
	global_load_dword v0, v[18:19], off
	v_lshl_add_u32 v18, v26, 2, 0
	s_movk_i32 s8, 0x410
	v_mad_u32_u24 v19, v36, s8, v18
	s_movk_i32 s8, 0x104
	s_waitcnt vmcnt(0)
	s_nop 4
	v_add_f32_e32 v2, v0, v2
	ds_write_b32 v19, v2 offset:18432
	v_add_f32_e32 v2, v0, v3
	v_mad_u32_u24 v3, v30, s8, v18
	v_add_f32_e32 v4, v0, v4
	v_add_u32_e32 v18, 0x4800, v3
	ds_write2_b32 v18, v2, v4 offset1:65
	v_add_f32_e32 v2, v0, v5
	ds_write_b32 v3, v2 offset:18952
	v_add_f32_e32 v2, v0, v6
	v_add_f32_e32 v4, v0, v7
	v_add_u32_e32 v5, 0x4e00, v3
	ds_write2_b32 v5, v2, v4 offset0:71 offset1:136
	v_add_f32_e32 v2, v0, v8
	v_add_f32_e32 v4, v0, v9
	v_add_u32_e32 v5, 0x5000, v3
	ds_write2_b32 v5, v2, v4 offset0:73 offset1:138
	v_add_f32_e32 v2, v0, v10
	v_add_f32_e32 v4, v0, v11
	v_add_u32_e32 v5, 0x5600, v3
	ds_write2_b32 v5, v2, v4 offset0:79 offset1:144
	v_add_f32_e32 v2, v0, v12
	v_add_f32_e32 v4, v0, v13
	v_add_u32_e32 v5, 0x5800, v3
	ds_write2_b32 v5, v2, v4 offset0:81 offset1:146
	v_add_f32_e32 v2, v0, v14
	v_add_f32_e32 v4, v0, v15
	v_add_u32_e32 v5, 0x5e00, v3
	ds_write2_b32 v5, v2, v4 offset0:87 offset1:152
	v_add_f32_e32 v2, v0, v16
	v_add_f32_e32 v0, v0, v17
	v_add_u32_e32 v3, 0x6000, v3
	ds_write2_b32 v3, v2, v0 offset0:89 offset1:154
